# phase 0 adaLN item: weight rows streamed continuously (each of the 16 row slots re-requested for the next batch right after its fma group; no per-batch latency bubble)
# speedup vs baseline: 1.0032x; 1.0022x over previous
; DI void adaln_item(const P& p, int a, unsigned char* smem) {
;     ...
;     const float* w = p.ada_w + (size_t)l * 2048 * 6144 + j0 + cg4;
;     f32x4 acc[5];
; #pragma unroll
;     for (int r = 0; r < 5; ++r) acc[r] = (f32x4){0.f, 0.f, 0.f, 0.f};
; #pragma unroll 1
;     for (int i0 = 0; i0 < 64; i0 += 16) {
;         f32x4 wv[16];
; #pragma unroll
;         for (int i = 0; i < 16; ++i) wv[i] = __builtin_nontemporal_load((const f32x4*)(w + (size_t)(kg + 32 * (i0 + i)) * 6144));
; #pragma unroll
;         for (int i = 0; i < 16; ++i) {
;             const int k = kg + 32 * (i0 + i);
; #pragma unroll
;             for (int r = 0; r < 5; ++r) acc[r] += wv[i] * sc[r * 2048 + k];
;         }
;     }
.LBB0_38:
	s_or_b64 exec, exec, s[26:27]
	s_mul_i32 s6, s63, 0x60
	s_add_i32 s26, s6, s64
	s_mul_hi_i32 s6, s26, 0x2aaaaaab
	s_lshr_b32 s27, s6, 31
	s_ashr_i32 s6, s6, 4
	s_add_i32 s6, s6, s27
	s_mul_i32 s27, s6, 0x60
	s_sub_i32 s26, s26, s27
	v_ashrrev_i32_e32 v76, 4, v78
	s_lshl_b32 s26, s26, 6
	v_mad_i64_i32 v[0:1], s[28:29], v76, s42, 0
	s_ashr_i32 s27, s26, 31
	v_mad_i64_i32 v[0:1], s[28:29], s6, v99, v[0:1]
	s_lshl_b64 s[28:29], s[26:27], 2
	v_and_b32_e32 v2, 15, v78
	s_add_u32 s28, s34, s28
	v_lshl_or_b32 v0, v2, 4, v0
	s_addc_u32 s29, s35, s29
	v_lshl_add_u64 v[80:81], s[28:29], 0, v[0:1]
	v_mov_b32_e32 v0, 0
	v_lshl_add_u32 v79, v76, 2, s62
	s_mov_b32 s27, -16
	v_mov_b32_e32 v1, v0
	v_mov_b32_e32 v2, v0
	v_mov_b32_e32 v3, v0
	v_mov_b32_e32 v4, v0
	v_mov_b32_e32 v5, v0
	v_mov_b32_e32 v6, v0
	v_mov_b32_e32 v7, v0
	v_mov_b32_e32 v8, v0
	v_mov_b32_e32 v9, v0
	v_mov_b32_e32 v10, v0
	v_mov_b32_e32 v11, v0
	v_mov_b32_e32 v12, v0
	v_mov_b32_e32 v13, v0
	v_mov_b32_e32 v14, v0
	v_mov_b32_e32 v15, v0
	v_mov_b32_e32 v16, v0
	v_mov_b32_e32 v17, v0
	v_mov_b32_e32 v18, v0
	v_mov_b32_e32 v19, v0
	s_waitcnt lgkmcnt(0)
	s_barrier
	v_add_co_u32_e32 v102, vcc, s43, v80
	s_nop 1
	v_addc_co_u32_e32 v103, vcc, -1, v81, vcc
	global_load_dwordx4 v[102:105], v[102:103], off nt
	v_add_co_u32_e32 v106, vcc, s44, v80
	s_nop 1
	v_addc_co_u32_e32 v107, vcc, -1, v81, vcc
	global_load_dwordx4 v[106:109], v[106:107], off nt
	v_add_co_u32_e32 v72, vcc, s45, v80
	s_nop 1
	v_addc_co_u32_e32 v73, vcc, -1, v81, vcc
	global_load_dwordx4 v[72:75], v[72:73], off nt
	v_add_co_u32_e32 v68, vcc, s46, v80
	s_nop 1
	v_addc_co_u32_e32 v69, vcc, -1, v81, vcc
	global_load_dwordx4 v[68:71], v[68:69], off nt
	v_add_co_u32_e32 v64, vcc, s47, v80
	s_nop 1
	v_addc_co_u32_e32 v65, vcc, -1, v81, vcc
	global_load_dwordx4 v[64:67], v[64:65], off nt
	v_add_co_u32_e32 v56, vcc, s48, v80
	s_nop 1
	v_addc_co_u32_e32 v57, vcc, -1, v81, vcc
	global_load_dwordx4 v[56:59], v[56:57], off nt
	v_add_co_u32_e32 v60, vcc, s49, v80
	s_nop 1
	v_addc_co_u32_e32 v61, vcc, -1, v81, vcc
	global_load_dwordx4 v[60:63], v[60:61], off nt
	v_add_co_u32_e32 v52, vcc, s51, v80
	s_nop 1
	v_addc_co_u32_e32 v53, vcc, -1, v81, vcc
	global_load_dwordx4 v[52:55], v[52:53], off nt
	v_add_co_u32_e32 v48, vcc, s52, v80
	s_nop 1
	v_addc_co_u32_e32 v49, vcc, -1, v81, vcc
	global_load_dwordx4 v[48:51], v[48:49], off nt
	v_add_co_u32_e32 v44, vcc, s53, v80
	s_nop 1
	v_addc_co_u32_e32 v45, vcc, -1, v81, vcc
	global_load_dwordx4 v[44:47], v[44:45], off nt
	v_add_co_u32_e32 v36, vcc, s54, v80
	s_nop 1
	v_addc_co_u32_e32 v37, vcc, -1, v81, vcc
	global_load_dwordx4 v[36:39], v[36:37], off nt
	v_add_co_u32_e32 v28, vcc, s55, v80
	s_nop 1
	v_addc_co_u32_e32 v29, vcc, -1, v81, vcc
	global_load_dwordx4 v[28:31], v[28:29], off nt
	v_add_co_u32_e32 v40, vcc, s56, v80
	s_nop 1
	v_addc_co_u32_e32 v41, vcc, -1, v81, vcc
	global_load_dwordx4 v[40:43], v[40:41], off nt
	v_add_co_u32_e32 v32, vcc, s57, v80
	s_nop 1
	v_addc_co_u32_e32 v33, vcc, -1, v81, vcc
	global_load_dwordx4 v[32:35], v[32:33], off nt
	v_add_co_u32_e32 v24, vcc, s58, v80
	s_nop 1
	v_addc_co_u32_e32 v25, vcc, -1, v81, vcc
	global_load_dwordx4 v[24:27], v[24:25], off nt
	global_load_dwordx4 v[20:23], v[80:81], off nt
.LBB0_39:
	ds_read2_b32 v[82:83], v79 offset1:32
	s_nop 0
	ds_read2_b32 v[84:85], v79 offset0:64 offset1:96
	ds_read2_b32 v[86:87], v79 offset0:128 offset1:160
	ds_read2_b32 v[88:89], v79 offset0:192 offset1:224
	v_add_u32_e32 v100, 0x2000, v79
	s_nop 0
	v_add_u32_e32 v101, 0x4000, v79
	s_nop 0
	v_add_u32_e32 v96, 0x6000, v79
	s_nop 0
	v_add_u32_e32 v98, 0x8000, v79
	s_nop 0
	ds_read2_b32 v[110:111], v100 offset1:32
	ds_read2_b32 v[112:113], v101 offset1:32
	ds_read2_b32 v[114:115], v96 offset1:32
	ds_read2_b32 v[116:117], v98 offset1:32
	s_waitcnt lgkmcnt(7)
	v_mov_b32_e32 v176, v83
	s_waitcnt lgkmcnt(3)
	v_mov_b32_e32 v184, v111
	s_waitcnt lgkmcnt(2)
	v_mov_b32_e32 v186, v113
	s_waitcnt lgkmcnt(1)
	v_mov_b32_e32 v188, v115
	s_nop 0
	ds_read2_b32 v[92:93], v100 offset0:64 offset1:96
	ds_read2_b32 v[94:95], v101 offset0:64 offset1:96
	ds_read2_b32 v[118:119], v96 offset0:64 offset1:96
	ds_read2_b32 v[120:121], v98 offset0:64 offset1:96
	s_waitcnt lgkmcnt(4)
	v_mov_b32_e32 v190, v117
	s_nop 0
	s_nop 0
	v_mov_b32_e32 v178, v85
	s_waitcnt lgkmcnt(3)
	v_mov_b32_e32 v192, v93
	s_waitcnt lgkmcnt(2)
	v_mov_b32_e32 v194, v95
	s_waitcnt lgkmcnt(1)
	v_mov_b32_e32 v196, v119
	s_waitcnt lgkmcnt(0)
	v_mov_b32_e32 v198, v121
	v_add_u32_e32 v164, 0x400, v79
	v_add_u32_e32 v168, 0x2400, v79
	v_add_u32_e32 v170, 0x4400, v79
	v_add_u32_e32 v172, 0x6400, v79
	v_add_u32_e32 v174, 0x8400, v79
	ds_read2_b32 v[90:91], v100 offset0:128 offset1:160
	ds_read2_b32 v[122:123], v101 offset0:128 offset1:160
	ds_read2_b32 v[124:125], v96 offset0:128 offset1:160
	ds_read2_b32 v[126:127], v98 offset0:128 offset1:160
	ds_read2_b32 v[128:129], v100 offset0:192 offset1:224
	ds_read2_b32 v[100:101], v101 offset0:192 offset1:224
	ds_read2_b32 v[130:131], v96 offset0:192 offset1:224
	ds_read2_b32 v[132:133], v98 offset0:192 offset1:224
	ds_read2_b32 v[134:135], v164 offset1:32
	ds_read2_b32 v[136:137], v168 offset1:32
	ds_read2_b32 v[138:139], v170 offset1:32
	ds_read2_b32 v[140:141], v172 offset1:32
	ds_read2_b32 v[142:143], v174 offset1:32
	ds_read2_b32 v[144:145], v164 offset0:64 offset1:96
	ds_read2_b32 v[146:147], v168 offset0:64 offset1:96
	ds_read2_b32 v[148:149], v170 offset0:64 offset1:96
	ds_read2_b32 v[150:151], v172 offset0:64 offset1:96
	ds_read2_b32 v[152:153], v174 offset0:64 offset1:96
	ds_read2_b32 v[154:155], v164 offset0:128 offset1:160
	ds_read2_b32 v[156:157], v168 offset0:128 offset1:160
	ds_read2_b32 v[158:159], v170 offset0:128 offset1:160
	ds_read2_b32 v[160:161], v172 offset0:128 offset1:160
	ds_read2_b32 v[162:163], v174 offset0:128 offset1:160
	ds_read2_b32 v[164:165], v164 offset0:192 offset1:224
	ds_read2_b32 v[168:169], v168 offset0:192 offset1:224
	ds_read2_b32 v[170:171], v170 offset0:192 offset1:224
	ds_read2_b32 v[172:173], v172 offset0:192 offset1:224
	ds_read2_b32 v[174:175], v174 offset0:192 offset1:224
	v_mov_b32_e32 v180, v87
	s_waitcnt lgkmcnt(14)
; DI void adaln_item(const P& p, int a, unsigned char* smem) {
;     ...
;         for (int i = 0; i < 16; ++i) {
;             const int k = kg + 32 * (i0 + i);
; #pragma unroll
;             for (int r = 0; r < 5; ++r) acc[r] += wv[i] * sc[r * 2048 + k];
	v_mov_b32_e32 v200, v91
	v_mov_b32_e32 v202, v123
	v_mov_b32_e32 v204, v125
	v_mov_b32_e32 v206, v127
	v_mov_b32_e32 v182, v89
	v_mov_b32_e32 v208, v129
	v_mov_b32_e32 v210, v101
	v_mov_b32_e32 v212, v131
	v_mov_b32_e32 v214, v133
	v_mov_b32_e32 v216, v135
	v_mov_b32_e32 v218, v137
	v_mov_b32_e32 v220, v139
	v_mov_b32_e32 v222, v141
	v_mov_b32_e32 v224, v143
	v_mov_b32_e32 v226, v145
	s_waitcnt lgkmcnt(13)
	v_mov_b32_e32 v228, v147
	s_waitcnt lgkmcnt(12)
	v_mov_b32_e32 v230, v149
	s_waitcnt lgkmcnt(11)
	v_mov_b32_e32 v232, v151
	s_waitcnt lgkmcnt(10)
	v_mov_b32_e32 v234, v153
	s_waitcnt vmcnt(15)
	v_pk_fma_f32 v[2:3], v[104:105], v[82:83], v[2:3] op_sel_hi:[1,0,1]
	v_pk_fma_f32 v[0:1], v[102:103], v[82:83], v[0:1] op_sel_hi:[1,0,1]
	v_pk_fma_f32 v[6:7], v[104:105], v[110:111], v[6:7] op_sel_hi:[1,0,1]
	v_pk_fma_f32 v[4:5], v[102:103], v[110:111], v[4:5] op_sel_hi:[1,0,1]
	v_pk_fma_f32 v[10:11], v[104:105], v[112:113], v[10:11] op_sel_hi:[1,0,1]
	v_pk_fma_f32 v[8:9], v[102:103], v[112:113], v[8:9] op_sel_hi:[1,0,1]
	v_pk_fma_f32 v[14:15], v[104:105], v[114:115], v[14:15] op_sel_hi:[1,0,1]
	v_pk_fma_f32 v[12:13], v[102:103], v[114:115], v[12:13] op_sel_hi:[1,0,1]
	v_pk_fma_f32 v[18:19], v[104:105], v[116:117], v[18:19] op_sel_hi:[1,0,1]
	v_pk_fma_f32 v[16:17], v[102:103], v[116:117], v[16:17] op_sel_hi:[1,0,1]
	v_add_co_u32_e32 v102, vcc, 0xc0000, v80
	s_nop 1
	v_addc_co_u32_e32 v103, vcc, 0, v81, vcc
	global_load_dwordx4 v[102:105], v[102:103], off nt
	s_waitcnt vmcnt(15)
	v_pk_fma_f32 v[2:3], v[108:109], v[176:177], v[2:3] op_sel_hi:[1,0,1]
	v_pk_fma_f32 v[0:1], v[106:107], v[176:177], v[0:1] op_sel_hi:[1,0,1]
	v_pk_fma_f32 v[6:7], v[108:109], v[184:185], v[6:7] op_sel_hi:[1,0,1]
	v_pk_fma_f32 v[4:5], v[106:107], v[184:185], v[4:5] op_sel_hi:[1,0,1]
	v_pk_fma_f32 v[10:11], v[108:109], v[186:187], v[10:11] op_sel_hi:[1,0,1]
	v_pk_fma_f32 v[8:9], v[106:107], v[186:187], v[8:9] op_sel_hi:[1,0,1]
	v_pk_fma_f32 v[14:15], v[108:109], v[188:189], v[14:15] op_sel_hi:[1,0,1]
	v_pk_fma_f32 v[12:13], v[106:107], v[188:189], v[12:13] op_sel_hi:[1,0,1]
	v_pk_fma_f32 v[18:19], v[108:109], v[190:191], v[18:19] op_sel_hi:[1,0,1]
	v_pk_fma_f32 v[16:17], v[106:107], v[190:191], v[16:17] op_sel_hi:[1,0,1]
	v_add_co_u32_e32 v106, vcc, 0x180000, v80
	s_nop 1
	v_addc_co_u32_e32 v107, vcc, 0, v81, vcc
	global_load_dwordx4 v[106:109], v[106:107], off nt
	s_waitcnt vmcnt(15)
	v_pk_fma_f32 v[2:3], v[74:75], v[84:85], v[2:3] op_sel_hi:[1,0,1]
	v_pk_fma_f32 v[0:1], v[72:73], v[84:85], v[0:1] op_sel_hi:[1,0,1]
	v_pk_fma_f32 v[6:7], v[74:75], v[92:93], v[6:7] op_sel_hi:[1,0,1]
	v_pk_fma_f32 v[4:5], v[72:73], v[92:93], v[4:5] op_sel_hi:[1,0,1]
	v_pk_fma_f32 v[10:11], v[74:75], v[94:95], v[10:11] op_sel_hi:[1,0,1]
	v_pk_fma_f32 v[8:9], v[72:73], v[94:95], v[8:9] op_sel_hi:[1,0,1]
	v_pk_fma_f32 v[14:15], v[74:75], v[118:119], v[14:15] op_sel_hi:[1,0,1]
	v_pk_fma_f32 v[12:13], v[72:73], v[118:119], v[12:13] op_sel_hi:[1,0,1]
	v_pk_fma_f32 v[18:19], v[74:75], v[120:121], v[18:19] op_sel_hi:[1,0,1]
	v_pk_fma_f32 v[16:17], v[72:73], v[120:121], v[16:17] op_sel_hi:[1,0,1]
	v_add_co_u32_e32 v72, vcc, 0x240000, v80
	s_nop 1
	v_addc_co_u32_e32 v73, vcc, 0, v81, vcc
	global_load_dwordx4 v[72:75], v[72:73], off nt
	s_waitcnt vmcnt(15)
	v_pk_fma_f32 v[2:3], v[70:71], v[178:179], v[2:3] op_sel_hi:[1,0,1]
	v_pk_fma_f32 v[0:1], v[68:69], v[178:179], v[0:1] op_sel_hi:[1,0,1]
	v_pk_fma_f32 v[6:7], v[70:71], v[192:193], v[6:7] op_sel_hi:[1,0,1]
	v_pk_fma_f32 v[4:5], v[68:69], v[192:193], v[4:5] op_sel_hi:[1,0,1]
	v_pk_fma_f32 v[10:11], v[70:71], v[194:195], v[10:11] op_sel_hi:[1,0,1]
	v_pk_fma_f32 v[8:9], v[68:69], v[194:195], v[8:9] op_sel_hi:[1,0,1]
	v_pk_fma_f32 v[14:15], v[70:71], v[196:197], v[14:15] op_sel_hi:[1,0,1]
	v_pk_fma_f32 v[12:13], v[68:69], v[196:197], v[12:13] op_sel_hi:[1,0,1]
	v_pk_fma_f32 v[18:19], v[70:71], v[198:199], v[18:19] op_sel_hi:[1,0,1]
	v_pk_fma_f32 v[16:17], v[68:69], v[198:199], v[16:17] op_sel_hi:[1,0,1]
	v_add_co_u32_e32 v68, vcc, 0x300000, v80
	s_nop 1
	v_addc_co_u32_e32 v69, vcc, 0, v81, vcc
	global_load_dwordx4 v[68:71], v[68:69], off nt
	s_waitcnt vmcnt(15)
	v_pk_fma_f32 v[2:3], v[66:67], v[86:87], v[2:3] op_sel_hi:[1,0,1]
	v_pk_fma_f32 v[0:1], v[64:65], v[86:87], v[0:1] op_sel_hi:[1,0,1]
	v_pk_fma_f32 v[6:7], v[66:67], v[90:91], v[6:7] op_sel_hi:[1,0,1]
	v_pk_fma_f32 v[4:5], v[64:65], v[90:91], v[4:5] op_sel_hi:[1,0,1]
	v_pk_fma_f32 v[10:11], v[66:67], v[122:123], v[10:11] op_sel_hi:[1,0,1]
	v_pk_fma_f32 v[8:9], v[64:65], v[122:123], v[8:9] op_sel_hi:[1,0,1]
	v_pk_fma_f32 v[14:15], v[66:67], v[124:125], v[14:15] op_sel_hi:[1,0,1]
	v_pk_fma_f32 v[12:13], v[64:65], v[124:125], v[12:13] op_sel_hi:[1,0,1]
	v_pk_fma_f32 v[18:19], v[66:67], v[126:127], v[18:19] op_sel_hi:[1,0,1]
	v_pk_fma_f32 v[16:17], v[64:65], v[126:127], v[16:17] op_sel_hi:[1,0,1]
	v_add_co_u32_e32 v64, vcc, 0x3c0000, v80
	s_nop 1
	v_addc_co_u32_e32 v65, vcc, 0, v81, vcc
	global_load_dwordx4 v[64:67], v[64:65], off nt
	s_waitcnt vmcnt(15)
	v_pk_fma_f32 v[2:3], v[58:59], v[180:181], v[2:3] op_sel_hi:[1,0,1]
	v_pk_fma_f32 v[0:1], v[56:57], v[180:181], v[0:1] op_sel_hi:[1,0,1]
	v_pk_fma_f32 v[6:7], v[58:59], v[200:201], v[6:7] op_sel_hi:[1,0,1]
	v_pk_fma_f32 v[4:5], v[56:57], v[200:201], v[4:5] op_sel_hi:[1,0,1]
	v_pk_fma_f32 v[10:11], v[58:59], v[202:203], v[10:11] op_sel_hi:[1,0,1]
	v_pk_fma_f32 v[8:9], v[56:57], v[202:203], v[8:9] op_sel_hi:[1,0,1]
	v_pk_fma_f32 v[14:15], v[58:59], v[204:205], v[14:15] op_sel_hi:[1,0,1]
	v_pk_fma_f32 v[12:13], v[56:57], v[204:205], v[12:13] op_sel_hi:[1,0,1]
	v_pk_fma_f32 v[18:19], v[58:59], v[206:207], v[18:19] op_sel_hi:[1,0,1]
	v_pk_fma_f32 v[16:17], v[56:57], v[206:207], v[16:17] op_sel_hi:[1,0,1]
	v_add_co_u32_e32 v56, vcc, 0x480000, v80
	s_nop 1
	v_addc_co_u32_e32 v57, vcc, 0, v81, vcc
	global_load_dwordx4 v[56:59], v[56:57], off nt
	s_waitcnt vmcnt(15)
; DI void adaln_item(const P& p, int a, unsigned char* smem) {
;     ...
;         for (int i = 0; i < 16; ++i) {
;             const int k = kg + 32 * (i0 + i);
; #pragma unroll
;             for (int r = 0; r < 5; ++r) acc[r] += wv[i] * sc[r * 2048 + k];
	v_pk_fma_f32 v[2:3], v[62:63], v[88:89], v[2:3] op_sel_hi:[1,0,1]
	v_pk_fma_f32 v[0:1], v[60:61], v[88:89], v[0:1] op_sel_hi:[1,0,1]
	v_pk_fma_f32 v[6:7], v[62:63], v[128:129], v[6:7] op_sel_hi:[1,0,1]
	v_pk_fma_f32 v[4:5], v[60:61], v[128:129], v[4:5] op_sel_hi:[1,0,1]
	v_pk_fma_f32 v[10:11], v[62:63], v[100:101], v[10:11] op_sel_hi:[1,0,1]
	v_pk_fma_f32 v[8:9], v[60:61], v[100:101], v[8:9] op_sel_hi:[1,0,1]
	v_pk_fma_f32 v[14:15], v[62:63], v[130:131], v[14:15] op_sel_hi:[1,0,1]
	v_pk_fma_f32 v[12:13], v[60:61], v[130:131], v[12:13] op_sel_hi:[1,0,1]
	v_pk_fma_f32 v[18:19], v[62:63], v[132:133], v[18:19] op_sel_hi:[1,0,1]
	v_pk_fma_f32 v[16:17], v[60:61], v[132:133], v[16:17] op_sel_hi:[1,0,1]
	v_add_co_u32_e32 v60, vcc, 0x540000, v80
	s_nop 1
	v_addc_co_u32_e32 v61, vcc, 0, v81, vcc
	global_load_dwordx4 v[60:63], v[60:61], off nt
	s_waitcnt vmcnt(15)
	v_pk_fma_f32 v[2:3], v[54:55], v[182:183], v[2:3] op_sel_hi:[1,0,1]
	v_pk_fma_f32 v[0:1], v[52:53], v[182:183], v[0:1] op_sel_hi:[1,0,1]
	v_pk_fma_f32 v[6:7], v[54:55], v[208:209], v[6:7] op_sel_hi:[1,0,1]
	v_pk_fma_f32 v[4:5], v[52:53], v[208:209], v[4:5] op_sel_hi:[1,0,1]
	v_pk_fma_f32 v[10:11], v[54:55], v[210:211], v[10:11] op_sel_hi:[1,0,1]
	v_pk_fma_f32 v[8:9], v[52:53], v[210:211], v[8:9] op_sel_hi:[1,0,1]
	v_pk_fma_f32 v[14:15], v[54:55], v[212:213], v[14:15] op_sel_hi:[1,0,1]
	v_pk_fma_f32 v[12:13], v[52:53], v[212:213], v[12:13] op_sel_hi:[1,0,1]
	v_pk_fma_f32 v[18:19], v[54:55], v[214:215], v[18:19] op_sel_hi:[1,0,1]
	v_pk_fma_f32 v[16:17], v[52:53], v[214:215], v[16:17] op_sel_hi:[1,0,1]
	v_add_co_u32_e32 v52, vcc, 0x600000, v80
	s_nop 1
	v_addc_co_u32_e32 v53, vcc, 0, v81, vcc
	global_load_dwordx4 v[52:55], v[52:53], off nt
	s_waitcnt vmcnt(15)
	v_pk_fma_f32 v[2:3], v[50:51], v[134:135], v[2:3] op_sel_hi:[1,0,1]
	v_pk_fma_f32 v[0:1], v[48:49], v[134:135], v[0:1] op_sel_hi:[1,0,1]
	v_pk_fma_f32 v[6:7], v[50:51], v[136:137], v[6:7] op_sel_hi:[1,0,1]
	v_pk_fma_f32 v[4:5], v[48:49], v[136:137], v[4:5] op_sel_hi:[1,0,1]
	v_pk_fma_f32 v[10:11], v[50:51], v[138:139], v[10:11] op_sel_hi:[1,0,1]
	v_pk_fma_f32 v[8:9], v[48:49], v[138:139], v[8:9] op_sel_hi:[1,0,1]
	v_pk_fma_f32 v[14:15], v[50:51], v[140:141], v[14:15] op_sel_hi:[1,0,1]
	v_pk_fma_f32 v[12:13], v[48:49], v[140:141], v[12:13] op_sel_hi:[1,0,1]
	v_pk_fma_f32 v[18:19], v[50:51], v[142:143], v[18:19] op_sel_hi:[1,0,1]
	v_pk_fma_f32 v[16:17], v[48:49], v[142:143], v[16:17] op_sel_hi:[1,0,1]
	v_add_co_u32_e32 v48, vcc, 0x6c0000, v80
	s_nop 1
	v_addc_co_u32_e32 v49, vcc, 0, v81, vcc
	global_load_dwordx4 v[48:51], v[48:49], off nt
	s_waitcnt vmcnt(15)
	v_pk_fma_f32 v[2:3], v[46:47], v[216:217], v[2:3] op_sel_hi:[1,0,1]
	v_pk_fma_f32 v[0:1], v[44:45], v[216:217], v[0:1] op_sel_hi:[1,0,1]
	v_pk_fma_f32 v[6:7], v[46:47], v[218:219], v[6:7] op_sel_hi:[1,0,1]
	v_pk_fma_f32 v[4:5], v[44:45], v[218:219], v[4:5] op_sel_hi:[1,0,1]
	v_pk_fma_f32 v[10:11], v[46:47], v[220:221], v[10:11] op_sel_hi:[1,0,1]
	v_pk_fma_f32 v[8:9], v[44:45], v[220:221], v[8:9] op_sel_hi:[1,0,1]
	v_pk_fma_f32 v[14:15], v[46:47], v[222:223], v[14:15] op_sel_hi:[1,0,1]
	v_pk_fma_f32 v[12:13], v[44:45], v[222:223], v[12:13] op_sel_hi:[1,0,1]
	v_pk_fma_f32 v[18:19], v[46:47], v[224:225], v[18:19] op_sel_hi:[1,0,1]
	v_pk_fma_f32 v[16:17], v[44:45], v[224:225], v[16:17] op_sel_hi:[1,0,1]
	v_add_co_u32_e32 v44, vcc, 0x780000, v80
	s_nop 1
	v_addc_co_u32_e32 v45, vcc, 0, v81, vcc
	global_load_dwordx4 v[44:47], v[44:45], off nt
	s_waitcnt vmcnt(15)
	v_pk_fma_f32 v[2:3], v[38:39], v[144:145], v[2:3] op_sel_hi:[1,0,1]
	v_pk_fma_f32 v[0:1], v[36:37], v[144:145], v[0:1] op_sel_hi:[1,0,1]
	v_pk_fma_f32 v[6:7], v[38:39], v[146:147], v[6:7] op_sel_hi:[1,0,1]
	v_pk_fma_f32 v[4:5], v[36:37], v[146:147], v[4:5] op_sel_hi:[1,0,1]
	v_pk_fma_f32 v[10:11], v[38:39], v[148:149], v[10:11] op_sel_hi:[1,0,1]
	v_pk_fma_f32 v[8:9], v[36:37], v[148:149], v[8:9] op_sel_hi:[1,0,1]
	v_pk_fma_f32 v[14:15], v[38:39], v[150:151], v[14:15] op_sel_hi:[1,0,1]
	v_pk_fma_f32 v[12:13], v[36:37], v[150:151], v[12:13] op_sel_hi:[1,0,1]
	v_pk_fma_f32 v[18:19], v[38:39], v[152:153], v[18:19] op_sel_hi:[1,0,1]
	v_pk_fma_f32 v[16:17], v[36:37], v[152:153], v[16:17] op_sel_hi:[1,0,1]
	v_add_co_u32_e32 v36, vcc, 0x840000, v80
	s_nop 1
	v_addc_co_u32_e32 v37, vcc, 0, v81, vcc
	global_load_dwordx4 v[36:39], v[36:37], off nt
	s_waitcnt vmcnt(15)
	v_pk_fma_f32 v[2:3], v[30:31], v[226:227], v[2:3] op_sel_hi:[1,0,1]
	v_pk_fma_f32 v[0:1], v[28:29], v[226:227], v[0:1] op_sel_hi:[1,0,1]
	v_pk_fma_f32 v[6:7], v[30:31], v[228:229], v[6:7] op_sel_hi:[1,0,1]
	v_pk_fma_f32 v[4:5], v[28:29], v[228:229], v[4:5] op_sel_hi:[1,0,1]
	v_pk_fma_f32 v[10:11], v[30:31], v[230:231], v[10:11] op_sel_hi:[1,0,1]
	v_pk_fma_f32 v[8:9], v[28:29], v[230:231], v[8:9] op_sel_hi:[1,0,1]
	v_pk_fma_f32 v[14:15], v[30:31], v[232:233], v[14:15] op_sel_hi:[1,0,1]
	v_pk_fma_f32 v[12:13], v[28:29], v[232:233], v[12:13] op_sel_hi:[1,0,1]
	v_pk_fma_f32 v[18:19], v[30:31], v[234:235], v[18:19] op_sel_hi:[1,0,1]
	v_pk_fma_f32 v[16:17], v[28:29], v[234:235], v[16:17] op_sel_hi:[1,0,1]
	v_add_co_u32_e32 v28, vcc, 0x900000, v80
	s_nop 1
	v_addc_co_u32_e32 v29, vcc, 0, v81, vcc
	global_load_dwordx4 v[28:31], v[28:29], off nt
	s_waitcnt lgkmcnt(9)
	v_mov_b32_e32 v236, v155
	s_waitcnt lgkmcnt(8)
	v_mov_b32_e32 v238, v157
	s_waitcnt lgkmcnt(7)
	v_mov_b32_e32 v240, v159
	s_waitcnt lgkmcnt(6)
	v_mov_b32_e32 v242, v161
	s_waitcnt lgkmcnt(5)
	v_mov_b32_e32 v244, v163
	s_waitcnt vmcnt(15)
; DI void adaln_item(const P& p, int a, unsigned char* smem) {
;     ...
;     for (int i0 = 0; i0 < 64; i0 += 16) {
;         f32x4 wv[16];
; #pragma unroll
;         for (int i = 0; i < 16; ++i) wv[i] = __builtin_nontemporal_load((const f32x4*)(w + (size_t)(kg + 32 * (i0 + i)) * 6144));
; #pragma unroll
;         for (int i = 0; i < 16; ++i) {
;             const int k = kg + 32 * (i0 + i);
; #pragma unroll
;             for (int r = 0; r < 5; ++r) acc[r] += wv[i] * sc[r * 2048 + k];
;         }
;     }
	v_pk_fma_f32 v[2:3], v[42:43], v[154:155], v[2:3] op_sel_hi:[1,0,1]
	v_pk_fma_f32 v[0:1], v[40:41], v[154:155], v[0:1] op_sel_hi:[1,0,1]
	v_pk_fma_f32 v[6:7], v[42:43], v[156:157], v[6:7] op_sel_hi:[1,0,1]
	v_pk_fma_f32 v[4:5], v[40:41], v[156:157], v[4:5] op_sel_hi:[1,0,1]
	v_pk_fma_f32 v[10:11], v[42:43], v[158:159], v[10:11] op_sel_hi:[1,0,1]
	v_pk_fma_f32 v[8:9], v[40:41], v[158:159], v[8:9] op_sel_hi:[1,0,1]
	v_pk_fma_f32 v[14:15], v[42:43], v[160:161], v[14:15] op_sel_hi:[1,0,1]
	v_pk_fma_f32 v[12:13], v[40:41], v[160:161], v[12:13] op_sel_hi:[1,0,1]
	v_pk_fma_f32 v[18:19], v[42:43], v[162:163], v[18:19] op_sel_hi:[1,0,1]
	v_pk_fma_f32 v[16:17], v[40:41], v[162:163], v[16:17] op_sel_hi:[1,0,1]
	v_add_co_u32_e32 v40, vcc, 0x9c0000, v80
	s_nop 1
	v_addc_co_u32_e32 v41, vcc, 0, v81, vcc
	global_load_dwordx4 v[40:43], v[40:41], off nt
	s_waitcnt vmcnt(15)
	v_pk_fma_f32 v[2:3], v[34:35], v[236:237], v[2:3] op_sel_hi:[1,0,1]
	v_pk_fma_f32 v[0:1], v[32:33], v[236:237], v[0:1] op_sel_hi:[1,0,1]
	v_pk_fma_f32 v[6:7], v[34:35], v[238:239], v[6:7] op_sel_hi:[1,0,1]
	v_pk_fma_f32 v[4:5], v[32:33], v[238:239], v[4:5] op_sel_hi:[1,0,1]
	v_pk_fma_f32 v[10:11], v[34:35], v[240:241], v[10:11] op_sel_hi:[1,0,1]
	v_pk_fma_f32 v[8:9], v[32:33], v[240:241], v[8:9] op_sel_hi:[1,0,1]
	v_pk_fma_f32 v[14:15], v[34:35], v[242:243], v[14:15] op_sel_hi:[1,0,1]
	v_pk_fma_f32 v[12:13], v[32:33], v[242:243], v[12:13] op_sel_hi:[1,0,1]
	v_pk_fma_f32 v[18:19], v[34:35], v[244:245], v[18:19] op_sel_hi:[1,0,1]
	v_pk_fma_f32 v[16:17], v[32:33], v[244:245], v[16:17] op_sel_hi:[1,0,1]
	v_add_co_u32_e32 v32, vcc, 0xa80000, v80
	s_nop 1
	v_addc_co_u32_e32 v33, vcc, 0, v81, vcc
	global_load_dwordx4 v[32:35], v[32:33], off nt
	s_add_i32 s27, s27, 16
	s_waitcnt lgkmcnt(4)
	v_mov_b32_e32 v246, v165
	s_waitcnt lgkmcnt(3)
	v_mov_b32_e32 v248, v169
	s_waitcnt lgkmcnt(2)
	v_mov_b32_e32 v250, v171
	s_waitcnt lgkmcnt(1)
	v_mov_b32_e32 v96, v173
	s_waitcnt lgkmcnt(0)
	v_mov_b32_e32 v98, v175
	s_waitcnt vmcnt(15)
	v_pk_fma_f32 v[2:3], v[26:27], v[164:165], v[2:3] op_sel_hi:[1,0,1]
	v_pk_fma_f32 v[0:1], v[24:25], v[164:165], v[0:1] op_sel_hi:[1,0,1]
	v_pk_fma_f32 v[6:7], v[26:27], v[168:169], v[6:7] op_sel_hi:[1,0,1]
	v_pk_fma_f32 v[4:5], v[24:25], v[168:169], v[4:5] op_sel_hi:[1,0,1]
	v_pk_fma_f32 v[10:11], v[26:27], v[170:171], v[10:11] op_sel_hi:[1,0,1]
	v_pk_fma_f32 v[8:9], v[24:25], v[170:171], v[8:9] op_sel_hi:[1,0,1]
	v_pk_fma_f32 v[14:15], v[26:27], v[172:173], v[14:15] op_sel_hi:[1,0,1]
	v_pk_fma_f32 v[12:13], v[24:25], v[172:173], v[12:13] op_sel_hi:[1,0,1]
	v_pk_fma_f32 v[18:19], v[26:27], v[174:175], v[18:19] op_sel_hi:[1,0,1]
	v_pk_fma_f32 v[16:17], v[24:25], v[174:175], v[16:17] op_sel_hi:[1,0,1]
	v_add_co_u32_e32 v24, vcc, 0xb40000, v80
	s_nop 1
	v_addc_co_u32_e32 v25, vcc, 0, v81, vcc
	global_load_dwordx4 v[24:27], v[24:25], off nt
	v_add_u32_e32 v79, 0x800, v79
	v_lshl_add_u64 v[80:81], v[80:81], 0, s[22:23]
	s_cmp_gt_u32 s27, 31
	s_waitcnt vmcnt(15)
	v_pk_fma_f32 v[2:3], v[22:23], v[246:247], v[2:3] op_sel_hi:[1,0,1]
	v_pk_fma_f32 v[0:1], v[20:21], v[246:247], v[0:1] op_sel_hi:[1,0,1]
	v_pk_fma_f32 v[6:7], v[22:23], v[248:249], v[6:7] op_sel_hi:[1,0,1]
	v_pk_fma_f32 v[4:5], v[20:21], v[248:249], v[4:5] op_sel_hi:[1,0,1]
	v_pk_fma_f32 v[10:11], v[22:23], v[250:251], v[10:11] op_sel_hi:[1,0,1]
	v_pk_fma_f32 v[8:9], v[20:21], v[250:251], v[8:9] op_sel_hi:[1,0,1]
	v_pk_fma_f32 v[14:15], v[22:23], v[96:97], v[14:15] op_sel_hi:[1,0,1]
	v_pk_fma_f32 v[12:13], v[20:21], v[96:97], v[12:13] op_sel_hi:[1,0,1]
	v_pk_fma_f32 v[18:19], v[22:23], v[98:99], v[18:19] op_sel_hi:[1,0,1]
	v_pk_fma_f32 v[16:17], v[20:21], v[98:99], v[16:17] op_sel_hi:[1,0,1]
	global_load_dwordx4 v[20:23], v[80:81], off nt
	s_cbranch_scc0 .LBB0_39
	ds_read2_b32 v[82:83], v79 offset1:32
	s_nop 0
	ds_read2_b32 v[84:85], v79 offset0:64 offset1:96
	ds_read2_b32 v[86:87], v79 offset0:128 offset1:160
	ds_read2_b32 v[88:89], v79 offset0:192 offset1:224
	v_add_u32_e32 v100, 0x2000, v79
	s_nop 0
	v_add_u32_e32 v101, 0x4000, v79
	s_nop 0
	v_add_u32_e32 v96, 0x6000, v79
	s_nop 0
	v_add_u32_e32 v98, 0x8000, v79
	s_nop 0
	ds_read2_b32 v[110:111], v100 offset1:32
	ds_read2_b32 v[112:113], v101 offset1:32
	ds_read2_b32 v[114:115], v96 offset1:32
	ds_read2_b32 v[116:117], v98 offset1:32
	s_waitcnt lgkmcnt(7)
	v_mov_b32_e32 v176, v83
	s_waitcnt lgkmcnt(3)
	v_mov_b32_e32 v184, v111
	s_waitcnt lgkmcnt(2)
	v_mov_b32_e32 v186, v113
	s_waitcnt lgkmcnt(1)
	v_mov_b32_e32 v188, v115
	s_nop 0
	ds_read2_b32 v[92:93], v100 offset0:64 offset1:96
	ds_read2_b32 v[94:95], v101 offset0:64 offset1:96
	ds_read2_b32 v[118:119], v96 offset0:64 offset1:96
	ds_read2_b32 v[120:121], v98 offset0:64 offset1:96
	s_waitcnt lgkmcnt(4)
	v_mov_b32_e32 v190, v117
	s_nop 0
	s_nop 0
	v_mov_b32_e32 v178, v85
	s_waitcnt lgkmcnt(3)
	v_mov_b32_e32 v192, v93
	s_waitcnt lgkmcnt(2)
	v_mov_b32_e32 v194, v95
	s_waitcnt lgkmcnt(1)
	v_mov_b32_e32 v196, v119
	s_waitcnt lgkmcnt(0)
; DI void adaln_item(const P& p, int a, unsigned char* smem) {
;     ...
;         for (int i = 0; i < 16; ++i) {
;             const int k = kg + 32 * (i0 + i);
; #pragma unroll
;             for (int r = 0; r < 5; ++r) acc[r] += wv[i] * sc[r * 2048 + k];
	v_mov_b32_e32 v198, v121
	v_add_u32_e32 v164, 0x400, v79
	v_add_u32_e32 v168, 0x2400, v79
	v_add_u32_e32 v170, 0x4400, v79
	v_add_u32_e32 v172, 0x6400, v79
	v_add_u32_e32 v174, 0x8400, v79
	ds_read2_b32 v[90:91], v100 offset0:128 offset1:160
	ds_read2_b32 v[122:123], v101 offset0:128 offset1:160
	ds_read2_b32 v[124:125], v96 offset0:128 offset1:160
	ds_read2_b32 v[126:127], v98 offset0:128 offset1:160
	ds_read2_b32 v[128:129], v100 offset0:192 offset1:224
	ds_read2_b32 v[100:101], v101 offset0:192 offset1:224
	ds_read2_b32 v[130:131], v96 offset0:192 offset1:224
	ds_read2_b32 v[132:133], v98 offset0:192 offset1:224
	ds_read2_b32 v[134:135], v164 offset1:32
	ds_read2_b32 v[136:137], v168 offset1:32
	ds_read2_b32 v[138:139], v170 offset1:32
	ds_read2_b32 v[140:141], v172 offset1:32
	ds_read2_b32 v[142:143], v174 offset1:32
	ds_read2_b32 v[144:145], v164 offset0:64 offset1:96
	ds_read2_b32 v[146:147], v168 offset0:64 offset1:96
	ds_read2_b32 v[148:149], v170 offset0:64 offset1:96
	ds_read2_b32 v[150:151], v172 offset0:64 offset1:96
	ds_read2_b32 v[152:153], v174 offset0:64 offset1:96
	ds_read2_b32 v[154:155], v164 offset0:128 offset1:160
	ds_read2_b32 v[156:157], v168 offset0:128 offset1:160
	ds_read2_b32 v[158:159], v170 offset0:128 offset1:160
	ds_read2_b32 v[160:161], v172 offset0:128 offset1:160
	ds_read2_b32 v[162:163], v174 offset0:128 offset1:160
	ds_read2_b32 v[164:165], v164 offset0:192 offset1:224
	ds_read2_b32 v[168:169], v168 offset0:192 offset1:224
	ds_read2_b32 v[170:171], v170 offset0:192 offset1:224
	ds_read2_b32 v[172:173], v172 offset0:192 offset1:224
	ds_read2_b32 v[174:175], v174 offset0:192 offset1:224
	v_mov_b32_e32 v180, v87
	s_waitcnt lgkmcnt(14)
	v_mov_b32_e32 v200, v91
	v_mov_b32_e32 v202, v123
	v_mov_b32_e32 v204, v125
	v_mov_b32_e32 v206, v127
	v_mov_b32_e32 v182, v89
	v_mov_b32_e32 v208, v129
	v_mov_b32_e32 v210, v101
	v_mov_b32_e32 v212, v131
	v_mov_b32_e32 v214, v133
	v_mov_b32_e32 v216, v135
	v_mov_b32_e32 v218, v137
	v_mov_b32_e32 v220, v139
	v_mov_b32_e32 v222, v141
	v_mov_b32_e32 v224, v143
	v_mov_b32_e32 v226, v145
	s_waitcnt lgkmcnt(13)
	v_mov_b32_e32 v228, v147
	s_waitcnt lgkmcnt(12)
	v_mov_b32_e32 v230, v149
	s_waitcnt lgkmcnt(11)
	v_mov_b32_e32 v232, v151
	s_waitcnt lgkmcnt(10)
	v_mov_b32_e32 v234, v153
	s_waitcnt vmcnt(15)
	v_pk_fma_f32 v[2:3], v[104:105], v[82:83], v[2:3] op_sel_hi:[1,0,1]
	v_pk_fma_f32 v[0:1], v[102:103], v[82:83], v[0:1] op_sel_hi:[1,0,1]
	v_pk_fma_f32 v[6:7], v[104:105], v[110:111], v[6:7] op_sel_hi:[1,0,1]
	v_pk_fma_f32 v[4:5], v[102:103], v[110:111], v[4:5] op_sel_hi:[1,0,1]
	v_pk_fma_f32 v[10:11], v[104:105], v[112:113], v[10:11] op_sel_hi:[1,0,1]
	v_pk_fma_f32 v[8:9], v[102:103], v[112:113], v[8:9] op_sel_hi:[1,0,1]
	v_pk_fma_f32 v[14:15], v[104:105], v[114:115], v[14:15] op_sel_hi:[1,0,1]
	v_pk_fma_f32 v[12:13], v[102:103], v[114:115], v[12:13] op_sel_hi:[1,0,1]
	v_pk_fma_f32 v[18:19], v[104:105], v[116:117], v[18:19] op_sel_hi:[1,0,1]
	v_pk_fma_f32 v[16:17], v[102:103], v[116:117], v[16:17] op_sel_hi:[1,0,1]
	s_waitcnt vmcnt(14)
	v_pk_fma_f32 v[2:3], v[108:109], v[176:177], v[2:3] op_sel_hi:[1,0,1]
	v_pk_fma_f32 v[0:1], v[106:107], v[176:177], v[0:1] op_sel_hi:[1,0,1]
	v_pk_fma_f32 v[6:7], v[108:109], v[184:185], v[6:7] op_sel_hi:[1,0,1]
	v_pk_fma_f32 v[4:5], v[106:107], v[184:185], v[4:5] op_sel_hi:[1,0,1]
	v_pk_fma_f32 v[10:11], v[108:109], v[186:187], v[10:11] op_sel_hi:[1,0,1]
	v_pk_fma_f32 v[8:9], v[106:107], v[186:187], v[8:9] op_sel_hi:[1,0,1]
	v_pk_fma_f32 v[14:15], v[108:109], v[188:189], v[14:15] op_sel_hi:[1,0,1]
	v_pk_fma_f32 v[12:13], v[106:107], v[188:189], v[12:13] op_sel_hi:[1,0,1]
	v_pk_fma_f32 v[18:19], v[108:109], v[190:191], v[18:19] op_sel_hi:[1,0,1]
	v_pk_fma_f32 v[16:17], v[106:107], v[190:191], v[16:17] op_sel_hi:[1,0,1]
	s_waitcnt vmcnt(13)
	v_pk_fma_f32 v[2:3], v[74:75], v[84:85], v[2:3] op_sel_hi:[1,0,1]
	v_pk_fma_f32 v[0:1], v[72:73], v[84:85], v[0:1] op_sel_hi:[1,0,1]
	v_pk_fma_f32 v[6:7], v[74:75], v[92:93], v[6:7] op_sel_hi:[1,0,1]
	v_pk_fma_f32 v[4:5], v[72:73], v[92:93], v[4:5] op_sel_hi:[1,0,1]
	v_pk_fma_f32 v[10:11], v[74:75], v[94:95], v[10:11] op_sel_hi:[1,0,1]
	v_pk_fma_f32 v[8:9], v[72:73], v[94:95], v[8:9] op_sel_hi:[1,0,1]
	v_pk_fma_f32 v[14:15], v[74:75], v[118:119], v[14:15] op_sel_hi:[1,0,1]
	v_pk_fma_f32 v[12:13], v[72:73], v[118:119], v[12:13] op_sel_hi:[1,0,1]
	v_pk_fma_f32 v[18:19], v[74:75], v[120:121], v[18:19] op_sel_hi:[1,0,1]
	v_pk_fma_f32 v[16:17], v[72:73], v[120:121], v[16:17] op_sel_hi:[1,0,1]
	s_waitcnt vmcnt(12)
	v_pk_fma_f32 v[2:3], v[70:71], v[178:179], v[2:3] op_sel_hi:[1,0,1]
	v_pk_fma_f32 v[0:1], v[68:69], v[178:179], v[0:1] op_sel_hi:[1,0,1]
	v_pk_fma_f32 v[6:7], v[70:71], v[192:193], v[6:7] op_sel_hi:[1,0,1]
	v_pk_fma_f32 v[4:5], v[68:69], v[192:193], v[4:5] op_sel_hi:[1,0,1]
	v_pk_fma_f32 v[10:11], v[70:71], v[194:195], v[10:11] op_sel_hi:[1,0,1]
	v_pk_fma_f32 v[8:9], v[68:69], v[194:195], v[8:9] op_sel_hi:[1,0,1]
	v_pk_fma_f32 v[14:15], v[70:71], v[196:197], v[14:15] op_sel_hi:[1,0,1]
	v_pk_fma_f32 v[12:13], v[68:69], v[196:197], v[12:13] op_sel_hi:[1,0,1]
	v_pk_fma_f32 v[18:19], v[70:71], v[198:199], v[18:19] op_sel_hi:[1,0,1]
	v_pk_fma_f32 v[16:17], v[68:69], v[198:199], v[16:17] op_sel_hi:[1,0,1]
	s_waitcnt vmcnt(11)
	v_pk_fma_f32 v[2:3], v[66:67], v[86:87], v[2:3] op_sel_hi:[1,0,1]
	v_pk_fma_f32 v[0:1], v[64:65], v[86:87], v[0:1] op_sel_hi:[1,0,1]
	v_pk_fma_f32 v[6:7], v[66:67], v[90:91], v[6:7] op_sel_hi:[1,0,1]
	v_pk_fma_f32 v[4:5], v[64:65], v[90:91], v[4:5] op_sel_hi:[1,0,1]
	v_pk_fma_f32 v[10:11], v[66:67], v[122:123], v[10:11] op_sel_hi:[1,0,1]
	v_pk_fma_f32 v[8:9], v[64:65], v[122:123], v[8:9] op_sel_hi:[1,0,1]
	v_pk_fma_f32 v[14:15], v[66:67], v[124:125], v[14:15] op_sel_hi:[1,0,1]
	v_pk_fma_f32 v[12:13], v[64:65], v[124:125], v[12:13] op_sel_hi:[1,0,1]
	v_pk_fma_f32 v[18:19], v[66:67], v[126:127], v[18:19] op_sel_hi:[1,0,1]
	v_pk_fma_f32 v[16:17], v[64:65], v[126:127], v[16:17] op_sel_hi:[1,0,1]
	s_waitcnt vmcnt(10)
; DI void adaln_item(const P& p, int a, unsigned char* smem) {
;     ...
;         for (int i = 0; i < 16; ++i) {
;             const int k = kg + 32 * (i0 + i);
; #pragma unroll
;             for (int r = 0; r < 5; ++r) acc[r] += wv[i] * sc[r * 2048 + k];
	v_pk_fma_f32 v[2:3], v[58:59], v[180:181], v[2:3] op_sel_hi:[1,0,1]
	v_pk_fma_f32 v[0:1], v[56:57], v[180:181], v[0:1] op_sel_hi:[1,0,1]
	v_pk_fma_f32 v[6:7], v[58:59], v[200:201], v[6:7] op_sel_hi:[1,0,1]
	v_pk_fma_f32 v[4:5], v[56:57], v[200:201], v[4:5] op_sel_hi:[1,0,1]
	v_pk_fma_f32 v[10:11], v[58:59], v[202:203], v[10:11] op_sel_hi:[1,0,1]
	v_pk_fma_f32 v[8:9], v[56:57], v[202:203], v[8:9] op_sel_hi:[1,0,1]
	v_pk_fma_f32 v[14:15], v[58:59], v[204:205], v[14:15] op_sel_hi:[1,0,1]
	v_pk_fma_f32 v[12:13], v[56:57], v[204:205], v[12:13] op_sel_hi:[1,0,1]
	v_pk_fma_f32 v[18:19], v[58:59], v[206:207], v[18:19] op_sel_hi:[1,0,1]
	v_pk_fma_f32 v[16:17], v[56:57], v[206:207], v[16:17] op_sel_hi:[1,0,1]
	s_waitcnt vmcnt(9)
	v_pk_fma_f32 v[2:3], v[62:63], v[88:89], v[2:3] op_sel_hi:[1,0,1]
	v_pk_fma_f32 v[0:1], v[60:61], v[88:89], v[0:1] op_sel_hi:[1,0,1]
	v_pk_fma_f32 v[6:7], v[62:63], v[128:129], v[6:7] op_sel_hi:[1,0,1]
	v_pk_fma_f32 v[4:5], v[60:61], v[128:129], v[4:5] op_sel_hi:[1,0,1]
	v_pk_fma_f32 v[10:11], v[62:63], v[100:101], v[10:11] op_sel_hi:[1,0,1]
	v_pk_fma_f32 v[8:9], v[60:61], v[100:101], v[8:9] op_sel_hi:[1,0,1]
	v_pk_fma_f32 v[14:15], v[62:63], v[130:131], v[14:15] op_sel_hi:[1,0,1]
	v_pk_fma_f32 v[12:13], v[60:61], v[130:131], v[12:13] op_sel_hi:[1,0,1]
	v_pk_fma_f32 v[18:19], v[62:63], v[132:133], v[18:19] op_sel_hi:[1,0,1]
	v_pk_fma_f32 v[16:17], v[60:61], v[132:133], v[16:17] op_sel_hi:[1,0,1]
	s_waitcnt vmcnt(8)
	v_pk_fma_f32 v[2:3], v[54:55], v[182:183], v[2:3] op_sel_hi:[1,0,1]
	v_pk_fma_f32 v[0:1], v[52:53], v[182:183], v[0:1] op_sel_hi:[1,0,1]
	v_pk_fma_f32 v[6:7], v[54:55], v[208:209], v[6:7] op_sel_hi:[1,0,1]
	v_pk_fma_f32 v[4:5], v[52:53], v[208:209], v[4:5] op_sel_hi:[1,0,1]
	v_pk_fma_f32 v[10:11], v[54:55], v[210:211], v[10:11] op_sel_hi:[1,0,1]
	v_pk_fma_f32 v[8:9], v[52:53], v[210:211], v[8:9] op_sel_hi:[1,0,1]
	v_pk_fma_f32 v[14:15], v[54:55], v[212:213], v[14:15] op_sel_hi:[1,0,1]
	v_pk_fma_f32 v[12:13], v[52:53], v[212:213], v[12:13] op_sel_hi:[1,0,1]
	v_pk_fma_f32 v[18:19], v[54:55], v[214:215], v[18:19] op_sel_hi:[1,0,1]
	v_pk_fma_f32 v[16:17], v[52:53], v[214:215], v[16:17] op_sel_hi:[1,0,1]
	s_waitcnt vmcnt(7)
	v_pk_fma_f32 v[2:3], v[50:51], v[134:135], v[2:3] op_sel_hi:[1,0,1]
	v_pk_fma_f32 v[0:1], v[48:49], v[134:135], v[0:1] op_sel_hi:[1,0,1]
	v_pk_fma_f32 v[6:7], v[50:51], v[136:137], v[6:7] op_sel_hi:[1,0,1]
	v_pk_fma_f32 v[4:5], v[48:49], v[136:137], v[4:5] op_sel_hi:[1,0,1]
	v_pk_fma_f32 v[10:11], v[50:51], v[138:139], v[10:11] op_sel_hi:[1,0,1]
	v_pk_fma_f32 v[8:9], v[48:49], v[138:139], v[8:9] op_sel_hi:[1,0,1]
	v_pk_fma_f32 v[14:15], v[50:51], v[140:141], v[14:15] op_sel_hi:[1,0,1]
	v_pk_fma_f32 v[12:13], v[48:49], v[140:141], v[12:13] op_sel_hi:[1,0,1]
	v_pk_fma_f32 v[18:19], v[50:51], v[142:143], v[18:19] op_sel_hi:[1,0,1]
	v_pk_fma_f32 v[16:17], v[48:49], v[142:143], v[16:17] op_sel_hi:[1,0,1]
	s_waitcnt vmcnt(6)
	v_pk_fma_f32 v[2:3], v[46:47], v[216:217], v[2:3] op_sel_hi:[1,0,1]
	v_pk_fma_f32 v[0:1], v[44:45], v[216:217], v[0:1] op_sel_hi:[1,0,1]
	v_pk_fma_f32 v[6:7], v[46:47], v[218:219], v[6:7] op_sel_hi:[1,0,1]
	v_pk_fma_f32 v[4:5], v[44:45], v[218:219], v[4:5] op_sel_hi:[1,0,1]
	v_pk_fma_f32 v[10:11], v[46:47], v[220:221], v[10:11] op_sel_hi:[1,0,1]
	v_pk_fma_f32 v[8:9], v[44:45], v[220:221], v[8:9] op_sel_hi:[1,0,1]
	v_pk_fma_f32 v[14:15], v[46:47], v[222:223], v[14:15] op_sel_hi:[1,0,1]
	v_pk_fma_f32 v[12:13], v[44:45], v[222:223], v[12:13] op_sel_hi:[1,0,1]
	v_pk_fma_f32 v[18:19], v[46:47], v[224:225], v[18:19] op_sel_hi:[1,0,1]
	v_pk_fma_f32 v[16:17], v[44:45], v[224:225], v[16:17] op_sel_hi:[1,0,1]
	s_waitcnt vmcnt(5)
	v_pk_fma_f32 v[2:3], v[38:39], v[144:145], v[2:3] op_sel_hi:[1,0,1]
	v_pk_fma_f32 v[0:1], v[36:37], v[144:145], v[0:1] op_sel_hi:[1,0,1]
	v_pk_fma_f32 v[6:7], v[38:39], v[146:147], v[6:7] op_sel_hi:[1,0,1]
	v_pk_fma_f32 v[4:5], v[36:37], v[146:147], v[4:5] op_sel_hi:[1,0,1]
	v_pk_fma_f32 v[10:11], v[38:39], v[148:149], v[10:11] op_sel_hi:[1,0,1]
	v_pk_fma_f32 v[8:9], v[36:37], v[148:149], v[8:9] op_sel_hi:[1,0,1]
	v_pk_fma_f32 v[14:15], v[38:39], v[150:151], v[14:15] op_sel_hi:[1,0,1]
	v_pk_fma_f32 v[12:13], v[36:37], v[150:151], v[12:13] op_sel_hi:[1,0,1]
	v_pk_fma_f32 v[18:19], v[38:39], v[152:153], v[18:19] op_sel_hi:[1,0,1]
	v_pk_fma_f32 v[16:17], v[36:37], v[152:153], v[16:17] op_sel_hi:[1,0,1]
	s_waitcnt vmcnt(4)
	v_pk_fma_f32 v[2:3], v[30:31], v[226:227], v[2:3] op_sel_hi:[1,0,1]
	v_pk_fma_f32 v[0:1], v[28:29], v[226:227], v[0:1] op_sel_hi:[1,0,1]
	v_pk_fma_f32 v[6:7], v[30:31], v[228:229], v[6:7] op_sel_hi:[1,0,1]
	v_pk_fma_f32 v[4:5], v[28:29], v[228:229], v[4:5] op_sel_hi:[1,0,1]
	v_pk_fma_f32 v[10:11], v[30:31], v[230:231], v[10:11] op_sel_hi:[1,0,1]
	v_pk_fma_f32 v[8:9], v[28:29], v[230:231], v[8:9] op_sel_hi:[1,0,1]
	v_pk_fma_f32 v[14:15], v[30:31], v[232:233], v[14:15] op_sel_hi:[1,0,1]
	v_pk_fma_f32 v[12:13], v[28:29], v[232:233], v[12:13] op_sel_hi:[1,0,1]
	v_pk_fma_f32 v[18:19], v[30:31], v[234:235], v[18:19] op_sel_hi:[1,0,1]
	v_pk_fma_f32 v[16:17], v[28:29], v[234:235], v[16:17] op_sel_hi:[1,0,1]
	s_waitcnt lgkmcnt(9)
	v_mov_b32_e32 v236, v155
	s_waitcnt lgkmcnt(8)
	v_mov_b32_e32 v238, v157
	s_waitcnt lgkmcnt(7)
	v_mov_b32_e32 v240, v159
	s_waitcnt lgkmcnt(6)
	v_mov_b32_e32 v242, v161
	s_waitcnt lgkmcnt(5)
	v_mov_b32_e32 v244, v163
	s_waitcnt vmcnt(3)
; DI void adaln_item(const P& p, int a, unsigned char* smem) {
;     ...
;         for (int i = 0; i < 16; ++i) {
;             const int k = kg + 32 * (i0 + i);
; #pragma unroll
;             for (int r = 0; r < 5; ++r) acc[r] += wv[i] * sc[r * 2048 + k];
;         }
;     }
; #pragma unroll
;     for (int r = 0; r < 5; ++r) *(f32x4*)(red + (kg * 5 + r) * 64 + cg4) = acc[r];
;     __syncthreads();
;     if (tid < 320) {
;         const int r = tid >> 6, tx = tid & 63; float sum = 0.f;
; #pragma unroll
;         for (int k2 = 0; k2 < 32; ++k2) sum += red[(k2 * 5 + r) * 64 + tx];
;         mod[(l * 5 + r) * 6144 + j0 + tx] = sum + p.ada_b[l * 6144 + j0 + tx];
;     }
;     __syncthreads();
	v_pk_fma_f32 v[2:3], v[42:43], v[154:155], v[2:3] op_sel_hi:[1,0,1]
	v_pk_fma_f32 v[0:1], v[40:41], v[154:155], v[0:1] op_sel_hi:[1,0,1]
	v_pk_fma_f32 v[6:7], v[42:43], v[156:157], v[6:7] op_sel_hi:[1,0,1]
	v_pk_fma_f32 v[4:5], v[40:41], v[156:157], v[4:5] op_sel_hi:[1,0,1]
	v_pk_fma_f32 v[10:11], v[42:43], v[158:159], v[10:11] op_sel_hi:[1,0,1]
	v_pk_fma_f32 v[8:9], v[40:41], v[158:159], v[8:9] op_sel_hi:[1,0,1]
	v_pk_fma_f32 v[14:15], v[42:43], v[160:161], v[14:15] op_sel_hi:[1,0,1]
	v_pk_fma_f32 v[12:13], v[40:41], v[160:161], v[12:13] op_sel_hi:[1,0,1]
	v_pk_fma_f32 v[18:19], v[42:43], v[162:163], v[18:19] op_sel_hi:[1,0,1]
	v_pk_fma_f32 v[16:17], v[40:41], v[162:163], v[16:17] op_sel_hi:[1,0,1]
	s_waitcnt vmcnt(2)
	v_pk_fma_f32 v[2:3], v[34:35], v[236:237], v[2:3] op_sel_hi:[1,0,1]
	v_pk_fma_f32 v[0:1], v[32:33], v[236:237], v[0:1] op_sel_hi:[1,0,1]
	v_pk_fma_f32 v[6:7], v[34:35], v[238:239], v[6:7] op_sel_hi:[1,0,1]
	v_pk_fma_f32 v[4:5], v[32:33], v[238:239], v[4:5] op_sel_hi:[1,0,1]
	v_pk_fma_f32 v[10:11], v[34:35], v[240:241], v[10:11] op_sel_hi:[1,0,1]
	v_pk_fma_f32 v[8:9], v[32:33], v[240:241], v[8:9] op_sel_hi:[1,0,1]
	v_pk_fma_f32 v[14:15], v[34:35], v[242:243], v[14:15] op_sel_hi:[1,0,1]
	v_pk_fma_f32 v[12:13], v[32:33], v[242:243], v[12:13] op_sel_hi:[1,0,1]
	v_pk_fma_f32 v[18:19], v[34:35], v[244:245], v[18:19] op_sel_hi:[1,0,1]
	v_pk_fma_f32 v[16:17], v[32:33], v[244:245], v[16:17] op_sel_hi:[1,0,1]
	s_add_i32 s27, s27, 16
	s_waitcnt lgkmcnt(4)
	v_mov_b32_e32 v246, v165
	s_waitcnt lgkmcnt(3)
	v_mov_b32_e32 v248, v169
	s_waitcnt lgkmcnt(2)
	v_mov_b32_e32 v250, v171
	s_waitcnt lgkmcnt(1)
	v_mov_b32_e32 v96, v173
	s_waitcnt lgkmcnt(0)
	v_mov_b32_e32 v98, v175
	s_waitcnt vmcnt(1)
	v_pk_fma_f32 v[2:3], v[26:27], v[164:165], v[2:3] op_sel_hi:[1,0,1]
	v_pk_fma_f32 v[0:1], v[24:25], v[164:165], v[0:1] op_sel_hi:[1,0,1]
	v_pk_fma_f32 v[6:7], v[26:27], v[168:169], v[6:7] op_sel_hi:[1,0,1]
	v_pk_fma_f32 v[4:5], v[24:25], v[168:169], v[4:5] op_sel_hi:[1,0,1]
	v_pk_fma_f32 v[10:11], v[26:27], v[170:171], v[10:11] op_sel_hi:[1,0,1]
	v_pk_fma_f32 v[8:9], v[24:25], v[170:171], v[8:9] op_sel_hi:[1,0,1]
	v_pk_fma_f32 v[14:15], v[26:27], v[172:173], v[14:15] op_sel_hi:[1,0,1]
	v_pk_fma_f32 v[12:13], v[24:25], v[172:173], v[12:13] op_sel_hi:[1,0,1]
	v_pk_fma_f32 v[18:19], v[26:27], v[174:175], v[18:19] op_sel_hi:[1,0,1]
	v_pk_fma_f32 v[16:17], v[24:25], v[174:175], v[16:17] op_sel_hi:[1,0,1]
	v_add_u32_e32 v79, 0x800, v79
	v_lshl_add_u64 v[80:81], v[80:81], 0, s[22:23]
	s_cmp_gt_u32 s27, 47
	s_waitcnt vmcnt(0)
	v_pk_fma_f32 v[2:3], v[22:23], v[246:247], v[2:3] op_sel_hi:[1,0,1]
	v_pk_fma_f32 v[0:1], v[20:21], v[246:247], v[0:1] op_sel_hi:[1,0,1]
	v_pk_fma_f32 v[6:7], v[22:23], v[248:249], v[6:7] op_sel_hi:[1,0,1]
	v_pk_fma_f32 v[4:5], v[20:21], v[248:249], v[4:5] op_sel_hi:[1,0,1]
	v_pk_fma_f32 v[10:11], v[22:23], v[250:251], v[10:11] op_sel_hi:[1,0,1]
	v_pk_fma_f32 v[8:9], v[20:21], v[250:251], v[8:9] op_sel_hi:[1,0,1]
	v_pk_fma_f32 v[14:15], v[22:23], v[96:97], v[14:15] op_sel_hi:[1,0,1]
	v_pk_fma_f32 v[12:13], v[20:21], v[96:97], v[12:13] op_sel_hi:[1,0,1]
	v_pk_fma_f32 v[18:19], v[22:23], v[98:99], v[18:19] op_sel_hi:[1,0,1]
	v_pk_fma_f32 v[16:17], v[20:21], v[98:99], v[16:17] op_sel_hi:[1,0,1]
	v_and_b32_e32 v20, 60, v177
	v_lshlrev_b32_e32 v20, 2, v20
	v_mul_lo_u32 v21, v76, s59
	v_add3_u32 v20, s62, v20, v21
	v_cmp_gt_i32_e32 vcc, s60, v78
	ds_write_b128 v20, v[0:3] offset:40960
	ds_write_b128 v20, v[4:7] offset:41216
	ds_write_b128 v20, v[8:11] offset:41472
	ds_write_b128 v20, v[12:15] offset:41728
	ds_write_b128 v20, v[16:19] offset:41984
	s_waitcnt lgkmcnt(0)
	s_barrier
	s_and_saveexec_b64 s[28:29], vcc
	s_cbranch_execz .LBB0_19
	s_mul_i32 s27, s6, 0x1800
	v_and_b32_e32 v30, 63, v78
	s_add_i32 s27, s27, s26
	v_or_b32_e32 v0, s27, v30
	v_ashrrev_i32_e32 v1, 31, v0
	v_lshl_add_u64 v[0:1], v[0:1], 2, s[18:19]
	global_load_dword v32, v[0:1], off
	v_and_b32_e32 v1, 0x3fffffc0, v78
	v_lshrrev_b32_e32 v0, 6, v78
	v_lshlrev_b32_e32 v2, 2, v1
	v_lshlrev_b32_e32 v3, 2, v30
	v_mad_u64_u32 v[0:1], s[64:65], s6, 5, v[0:1]
	v_add3_u32 v19, s62, v2, v3
	v_lshl_add_u32 v18, v78, 2, s62
	v_mul_lo_u32 v20, v0, s61
	ds_read2st64_b32 v[0:1], v19 offset0:165 offset1:170
	ds_read2st64_b32 v[2:3], v19 offset0:175 offset1:180
	ds_read2st64_b32 v[4:5], v19 offset0:185 offset1:190
	ds_read2st64_b32 v[6:7], v19 offset0:195 offset1:200
	ds_read2st64_b32 v[8:9], v19 offset0:205 offset1:210
	ds_read2st64_b32 v[10:11], v19 offset0:215 offset1:220
	ds_read2st64_b32 v[12:13], v19 offset0:225 offset1:230
	ds_read2st64_b32 v[14:15], v19 offset0:235 offset1:240
	ds_read2st64_b32 v[16:17], v19 offset0:245 offset1:250
	ds_read_b32 v33, v18 offset:40960
	ds_read_b32 v34, v19 offset:65280
	v_add_u32_e32 v28, 0xa000, v19
	v_add_u32_e32 v31, s26, v20
	ds_read2st64_b32 v[18:19], v28 offset0:100 offset1:105
	ds_read2st64_b32 v[20:21], v28 offset0:110 offset1:115
	ds_read2st64_b32 v[22:23], v28 offset0:120 offset1:125
	ds_read2st64_b32 v[24:25], v28 offset0:130 offset1:135
	ds_read2st64_b32 v[26:27], v28 offset0:140 offset1:145
	ds_read2st64_b32 v[28:29], v28 offset0:150 offset1:155
	s_waitcnt lgkmcnt(7)
	v_add_f32_e32 v33, 0, v33
	v_add_f32_e32 v0, v33, v0
	v_add_f32_e32 v0, v0, v1
	v_add_f32_e32 v0, v0, v2
	v_add_f32_e32 v0, v0, v3
	v_add_f32_e32 v0, v0, v4
	v_add_f32_e32 v0, v0, v5
	v_add_f32_e32 v0, v0, v6
	v_add_f32_e32 v0, v0, v7
	v_add_f32_e32 v0, v0, v8
	v_add_f32_e32 v0, v0, v9
	v_add_f32_e32 v0, v0, v10
	v_add_f32_e32 v0, v0, v11
	v_add_f32_e32 v0, v0, v12
	v_add_f32_e32 v0, v0, v13
	v_add_f32_e32 v0, v0, v14
	v_add_f32_e32 v0, v0, v15
	v_add_f32_e32 v0, v0, v16
	v_add_f32_e32 v0, v0, v17
	s_waitcnt lgkmcnt(6)
	v_add_f32_e32 v0, v0, v34
	s_waitcnt lgkmcnt(5)
	v_add_f32_e32 v0, v0, v18
	v_add_f32_e32 v0, v0, v19
	s_waitcnt lgkmcnt(4)
	v_add_f32_e32 v0, v0, v20
	v_add_f32_e32 v0, v0, v21
	s_waitcnt lgkmcnt(3)
	v_add_f32_e32 v0, v0, v22
	v_add_f32_e32 v0, v0, v23
	s_waitcnt lgkmcnt(2)
	v_add_f32_e32 v0, v0, v24
	v_add_f32_e32 v0, v0, v25
	v_or_b32_e32 v30, v31, v30
	s_waitcnt lgkmcnt(1)
	v_add_f32_e32 v0, v0, v26
	v_ashrrev_i32_e32 v31, 31, v30
	v_add_f32_e32 v0, v0, v27
	v_lshl_add_u64 v[30:31], v[30:31], 2, s[24:25]
	s_waitcnt lgkmcnt(0)
	v_add_f32_e32 v0, v0, v28
	v_add_co_u32_e32 v30, vcc, 0x4800000, v30
	v_add_f32_e32 v0, v0, v29
	s_nop 0
	v_addc_co_u32_e32 v31, vcc, 0, v31, vcc
	s_waitcnt vmcnt(0)
	v_add_f32_e32 v0, v0, v32
	global_store_dword v[30:31], v0, off
	s_branch .LBB0_19
